# v13 + final RMSNorm and prologue rms_rows fast paths: next row prefetched into a second register set, exact vmcnt so earlier stores stay in flight
# speedup vs baseline: 1.0020x; 1.0001x over previous
; __global__ void __launch_bounds__(512, 2) fwd_kernel(Args a) {
;     ...
;             PH_LANES;
;             const float* gn = ap->in[I_NFIN];
;             for (int m = gw; m < MTOK; m += NGW) { const u32x4* hr = (const u32x4*)(H + (size_t)m * DMODEL) + lane; f32x4* xr = (f32x4*)(X + (size_t)m * DMODEL); float v[16]; float s = 0.f;
; #pragma unroll
;                 for (int jj = 0; jj < 2; ++jj) { const u32x4 w = hr[64 * jj];
; #pragma unroll
;                     for (int k = 0; k < 4; ++k) { v[jj * 8 + 2 * k] = __uint_as_float(w[k] << 16); v[jj * 8 + 2 * k + 1] = __uint_as_float(w[k] & 0xffff0000u); } }
; #pragma unroll
;                 for (int k = 0; k < 16; ++k) s += v[k] * v[k];
;                 const float rstd = rsqrtf(wave_sum(s) * (1.0f / DMODEL) + EPS);
; #pragma unroll
;                 for (int jj = 0; jj < 2; ++jj) { const int c4 = 2 * (lane + 64 * jj); const f32x4 g0 = ((const f32x4*)gn)[c4], g1 = ((const f32x4*)gn)[c4 + 1];
;                     xr[c4] = (f32x4){v[jj * 8 + 0] * rstd * g0[0], v[jj * 8 + 1] * rstd * g0[1], v[jj * 8 + 2] * rstd * g0[2], v[jj * 8 + 3] * rstd * g0[3]};
;                     xr[c4 + 1] = (f32x4){v[jj * 8 + 4] * rstd * g1[0], v[jj * 8 + 5] * rstd * g1[1], v[jj * 8 + 6] * rstd * g1[2], v[jj * 8 + 7] * rstd * g1[3]}; } }
.LBB0_397:
	s_and_b64 vcc, exec, s[4:5]
	s_movk_i32 s24, 0x60
	s_mov_b32 s25, 0x2aaaaaab
	s_movk_i32 s45, 0xaff
	s_movk_i32 s47, 0xff00
	s_cbranch_vccz .LBB0_402
	s_lshl_b32 s0, s62, 3
	v_mbcnt_lo_u32_b32 v0, -1, 0
	v_mbcnt_hi_u32_b32 v0, -1, v0
	s_add_i32 s4, s0, s57
	v_readlane_b32 s72, v252, 13
	v_readlane_b32 s74, v252, 15
	v_add_u32_e32 v0, s33, v0
	s_cmp_gt_i32 s4, 0x13fff
	v_readlane_b32 s73, v252, 14
	v_readlane_b32 s75, v252, 16
	s_cbranch_scc1 .LBB0_402
	v_readlane_b32 s6, v252, 17
	v_readlane_b32 s7, v252, 18
	s_load_dwordx2 s[6:7], s[6:7], 0xd0
	v_and_b32_e32 v4, 63, v0
	s_ashr_i32 s5, s4, 31
	v_lshlrev_b32_e32 v0, 5, v4
	s_lshl_b64 s[8:9], s[4:5], 11
	s_waitcnt lgkmcnt(0)
	v_lshl_add_u64 v[2:3], s[6:7], 0, v[0:1]
	s_add_u32 s6, s60, s8
	v_lshlrev_b32_e32 v4, 4, v4
	v_mov_b32_e32 v5, v1
	s_addc_u32 s7, s61, s9
	s_ashr_i32 s55, s54, 31
	v_lshl_add_u64 v[4:5], s[6:7], 0, v[4:5]
	s_lshl_b64 s[6:7], s[54:55], 11
	s_lshl_b64 s[8:9], s[4:5], 12
	v_readlane_b32 s16, v252, 21
	v_readlane_b32 s17, v252, 22
	s_add_u32 s8, s16, s8
	s_addc_u32 s9, s17, s9
	v_lshl_add_u64 v[6:7], s[8:9], 0, v[0:1]
	s_lshl_b64 s[8:9], s[54:55], 12
	v_readlane_b32 s18, v252, 23
	v_readlane_b32 s19, v252, 24
	s_cmpk_lg_i32 s54, 0x800
	s_cbranch_scc1 .LBB0_400
	global_load_dwordx4 v[48:51], v[2:3], off
	global_load_dwordx4 v[52:55], v[2:3], off offset:16
	global_load_dwordx4 v[56:59], v[2:3], off offset:2048
	global_load_dwordx4 v[60:63], v[2:3], off offset:2064
	global_load_dwordx4 v[8:11], v[4:5], off
	global_load_dwordx4 v[12:15], v[4:5], off offset:1024
	v_lshl_add_u64 v[4:5], v[4:5], 0, s[6:7]
	s_movk_i32 s10, 20
	global_load_dwordx4 v[64:67], v[4:5], off
	global_load_dwordx4 v[68:71], v[4:5], off offset:1024
	v_lshl_add_u64 v[4:5], v[4:5], 0, s[6:7]
	s_waitcnt vmcnt(2)
	s_branch .Lfin_first
.Lfin_loop:
	global_load_dwordx4 v[64:67], v[4:5], off
	global_load_dwordx4 v[68:71], v[4:5], off offset:1024
	v_lshl_add_u64 v[4:5], v[4:5], 0, s[6:7]
	s_waitcnt vmcnt(6)
.Lfin_first:
	v_lshlrev_b32_e32 v24, 16, v8
	v_and_b32_e32 v25, 0xffff0000, v8
	v_lshlrev_b32_e32 v26, 16, v9
	v_and_b32_e32 v27, 0xffff0000, v9
	v_lshlrev_b32_e32 v28, 16, v10
	v_and_b32_e32 v29, 0xffff0000, v10
	v_lshlrev_b32_e32 v30, 16, v11
	v_and_b32_e32 v31, 0xffff0000, v11
	v_lshlrev_b32_e32 v32, 16, v12
	v_and_b32_e32 v33, 0xffff0000, v12
	v_lshlrev_b32_e32 v34, 16, v13
	v_and_b32_e32 v35, 0xffff0000, v13
	v_lshlrev_b32_e32 v36, 16, v14
	v_and_b32_e32 v37, 0xffff0000, v14
	v_lshlrev_b32_e32 v38, 16, v15
	v_and_b32_e32 v39, 0xffff0000, v15
	v_pk_mul_f32 v[42:43], v[24:25], v[24:25]
	v_add_f32_e32 v40, v42, v43
	v_pk_mul_f32 v[42:43], v[26:27], v[26:27]
	v_add_f32_e32 v40, v40, v42
	v_add_f32_e32 v40, v40, v43
	v_pk_mul_f32 v[42:43], v[28:29], v[28:29]
	v_add_f32_e32 v40, v40, v42
	v_add_f32_e32 v40, v40, v43
	v_pk_mul_f32 v[42:43], v[30:31], v[30:31]
	v_add_f32_e32 v40, v40, v42
	v_add_f32_e32 v40, v40, v43
	v_pk_mul_f32 v[42:43], v[32:33], v[32:33]
	v_add_f32_e32 v40, v40, v42
	v_add_f32_e32 v40, v40, v43
	v_pk_mul_f32 v[42:43], v[34:35], v[34:35]
	v_add_f32_e32 v40, v40, v42
	v_add_f32_e32 v40, v40, v43
	v_pk_mul_f32 v[42:43], v[36:37], v[36:37]
	v_add_f32_e32 v40, v40, v42
	v_add_f32_e32 v40, v40, v43
	v_pk_mul_f32 v[42:43], v[38:39], v[38:39]
	v_add_f32_e32 v40, v40, v42
	v_add_f32_e32 v40, v40, v43
	ds_swizzle_b32 v41, v40 offset:swizzle(SWAP,1)
	s_waitcnt lgkmcnt(0)
	v_add_f32_e32 v40, v40, v41
	ds_swizzle_b32 v41, v40 offset:swizzle(SWAP,2)
	s_waitcnt lgkmcnt(0)
	v_add_f32_e32 v40, v40, v41
	ds_swizzle_b32 v41, v40 offset:swizzle(SWAP,4)
	s_waitcnt lgkmcnt(0)
	v_add_f32_e32 v40, v40, v41
	ds_swizzle_b32 v41, v40 offset:swizzle(SWAP,8)
	s_waitcnt lgkmcnt(0)
	v_add_f32_e32 v40, v40, v41
	ds_swizzle_b32 v41, v40 offset:swizzle(SWAP,16)
	s_waitcnt lgkmcnt(0)
	v_add_f32_e32 v40, v40, v41
	v_mov_b32_e32 v41, v40
	s_nop 1
	v_permlane32_swap_b32_e32 v40, v41
	v_add_f32_e32 v40, v40, v41
	v_fmamk_f32 v40, v40, 0x3a800000, v200
	v_rsq_f32_e32 v40, v40
	s_nop 0
	v_pk_mul_f32 v[24:25], v[40:41], v[24:25] op_sel_hi:[0,1]
	v_pk_mul_f32 v[26:27], v[40:41], v[26:27] op_sel_hi:[0,1]
	v_pk_mul_f32 v[28:29], v[40:41], v[28:29] op_sel_hi:[0,1]
	v_pk_mul_f32 v[30:31], v[40:41], v[30:31] op_sel_hi:[0,1]
	v_pk_mul_f32 v[32:33], v[40:41], v[32:33] op_sel_hi:[0,1]
	v_pk_mul_f32 v[34:35], v[40:41], v[34:35] op_sel_hi:[0,1]
	v_pk_mul_f32 v[36:37], v[40:41], v[36:37] op_sel_hi:[0,1]
	v_pk_mul_f32 v[38:39], v[40:41], v[38:39] op_sel_hi:[0,1]
	v_pk_mul_f32 v[24:25], v[48:49], v[24:25]
	v_pk_mul_f32 v[26:27], v[50:51], v[26:27]
	v_pk_mul_f32 v[28:29], v[52:53], v[28:29]
	v_pk_mul_f32 v[30:31], v[54:55], v[30:31]
	v_pk_mul_f32 v[32:33], v[56:57], v[32:33]
	v_pk_mul_f32 v[34:35], v[58:59], v[34:35]
	v_pk_mul_f32 v[36:37], v[60:61], v[36:37]
	v_pk_mul_f32 v[38:39], v[62:63], v[38:39]
	global_store_dwordx4 v[6:7], v[24:27], off
	global_store_dwordx4 v[6:7], v[28:31], off offset:16
	global_store_dwordx4 v[6:7], v[32:35], off offset:2048
	global_store_dwordx4 v[6:7], v[36:39], off offset:2064
	v_lshl_add_u64 v[6:7], v[6:7], 0, s[8:9]
	s_sub_i32 s10, s10, 1
	s_cmp_eq_u32 s10, 0
	s_cbranch_scc1 .Lfin_lastB
; __global__ void __launch_bounds__(512, 2) fwd_kernel(Args a) {
;     ...
;             PH_LANES;
;             const float* gn = ap->in[I_NFIN];
;             for (int m = gw; m < MTOK; m += NGW) { const u32x4* hr = (const u32x4*)(H + (size_t)m * DMODEL) + lane; f32x4* xr = (f32x4*)(X + (size_t)m * DMODEL); float v[16]; float s = 0.f;
; #pragma unroll
;                 for (int jj = 0; jj < 2; ++jj) { const u32x4 w = hr[64 * jj];
; #pragma unroll
;                     for (int k = 0; k < 4; ++k) { v[jj * 8 + 2 * k] = __uint_as_float(w[k] << 16); v[jj * 8 + 2 * k + 1] = __uint_as_float(w[k] & 0xffff0000u); } }
; #pragma unroll
;                 for (int k = 0; k < 16; ++k) s += v[k] * v[k];
;                 const float rstd = rsqrtf(wave_sum(s) * (1.0f / DMODEL) + EPS);
; #pragma unroll
;                 for (int jj = 0; jj < 2; ++jj) { const int c4 = 2 * (lane + 64 * jj); const f32x4 g0 = ((const f32x4*)gn)[c4], g1 = ((const f32x4*)gn)[c4 + 1];
;                     xr[c4] = (f32x4){v[jj * 8 + 0] * rstd * g0[0], v[jj * 8 + 1] * rstd * g0[1], v[jj * 8 + 2] * rstd * g0[2], v[jj * 8 + 3] * rstd * g0[3]};
;                     xr[c4 + 1] = (f32x4){v[jj * 8 + 4] * rstd * g1[0], v[jj * 8 + 5] * rstd * g1[1], v[jj * 8 + 6] * rstd * g1[2], v[jj * 8 + 7] * rstd * g1[3]}; } }
	global_load_dwordx4 v[8:11], v[4:5], off
	global_load_dwordx4 v[12:15], v[4:5], off offset:1024
	v_lshl_add_u64 v[4:5], v[4:5], 0, s[6:7]
	s_waitcnt vmcnt(6)
	v_lshlrev_b32_e32 v24, 16, v64
	v_and_b32_e32 v25, 0xffff0000, v64
	v_lshlrev_b32_e32 v26, 16, v65
	v_and_b32_e32 v27, 0xffff0000, v65
	v_lshlrev_b32_e32 v28, 16, v66
	v_and_b32_e32 v29, 0xffff0000, v66
	v_lshlrev_b32_e32 v30, 16, v67
	v_and_b32_e32 v31, 0xffff0000, v67
	v_lshlrev_b32_e32 v32, 16, v68
	v_and_b32_e32 v33, 0xffff0000, v68
	v_lshlrev_b32_e32 v34, 16, v69
	v_and_b32_e32 v35, 0xffff0000, v69
	v_lshlrev_b32_e32 v36, 16, v70
	v_and_b32_e32 v37, 0xffff0000, v70
	v_lshlrev_b32_e32 v38, 16, v71
	v_and_b32_e32 v39, 0xffff0000, v71
	v_pk_mul_f32 v[42:43], v[24:25], v[24:25]
	v_add_f32_e32 v40, v42, v43
	v_pk_mul_f32 v[42:43], v[26:27], v[26:27]
	v_add_f32_e32 v40, v40, v42
	v_add_f32_e32 v40, v40, v43
	v_pk_mul_f32 v[42:43], v[28:29], v[28:29]
	v_add_f32_e32 v40, v40, v42
	v_add_f32_e32 v40, v40, v43
	v_pk_mul_f32 v[42:43], v[30:31], v[30:31]
	v_add_f32_e32 v40, v40, v42
	v_add_f32_e32 v40, v40, v43
	v_pk_mul_f32 v[42:43], v[32:33], v[32:33]
	v_add_f32_e32 v40, v40, v42
	v_add_f32_e32 v40, v40, v43
	v_pk_mul_f32 v[42:43], v[34:35], v[34:35]
	v_add_f32_e32 v40, v40, v42
	v_add_f32_e32 v40, v40, v43
	v_pk_mul_f32 v[42:43], v[36:37], v[36:37]
	v_add_f32_e32 v40, v40, v42
	v_add_f32_e32 v40, v40, v43
	v_pk_mul_f32 v[42:43], v[38:39], v[38:39]
	v_add_f32_e32 v40, v40, v42
	v_add_f32_e32 v40, v40, v43
	ds_swizzle_b32 v41, v40 offset:swizzle(SWAP,1)
	s_waitcnt lgkmcnt(0)
	v_add_f32_e32 v40, v40, v41
	ds_swizzle_b32 v41, v40 offset:swizzle(SWAP,2)
	s_waitcnt lgkmcnt(0)
	v_add_f32_e32 v40, v40, v41
	ds_swizzle_b32 v41, v40 offset:swizzle(SWAP,4)
	s_waitcnt lgkmcnt(0)
	v_add_f32_e32 v40, v40, v41
	ds_swizzle_b32 v41, v40 offset:swizzle(SWAP,8)
	s_waitcnt lgkmcnt(0)
	v_add_f32_e32 v40, v40, v41
	ds_swizzle_b32 v41, v40 offset:swizzle(SWAP,16)
	s_waitcnt lgkmcnt(0)
	v_add_f32_e32 v40, v40, v41
	v_mov_b32_e32 v41, v40
	s_nop 1
	v_permlane32_swap_b32_e32 v40, v41
	v_add_f32_e32 v40, v40, v41
	v_fmamk_f32 v40, v40, 0x3a800000, v200
	v_rsq_f32_e32 v40, v40
	s_nop 0
	v_pk_mul_f32 v[24:25], v[40:41], v[24:25] op_sel_hi:[0,1]
	v_pk_mul_f32 v[26:27], v[40:41], v[26:27] op_sel_hi:[0,1]
	v_pk_mul_f32 v[28:29], v[40:41], v[28:29] op_sel_hi:[0,1]
	v_pk_mul_f32 v[30:31], v[40:41], v[30:31] op_sel_hi:[0,1]
	v_pk_mul_f32 v[32:33], v[40:41], v[32:33] op_sel_hi:[0,1]
	v_pk_mul_f32 v[34:35], v[40:41], v[34:35] op_sel_hi:[0,1]
	v_pk_mul_f32 v[36:37], v[40:41], v[36:37] op_sel_hi:[0,1]
	v_pk_mul_f32 v[38:39], v[40:41], v[38:39] op_sel_hi:[0,1]
	v_pk_mul_f32 v[24:25], v[48:49], v[24:25]
	v_pk_mul_f32 v[26:27], v[50:51], v[26:27]
	v_pk_mul_f32 v[28:29], v[52:53], v[28:29]
	v_pk_mul_f32 v[30:31], v[54:55], v[30:31]
	v_pk_mul_f32 v[32:33], v[56:57], v[32:33]
	v_pk_mul_f32 v[34:35], v[58:59], v[34:35]
	v_pk_mul_f32 v[36:37], v[60:61], v[36:37]
	v_pk_mul_f32 v[38:39], v[62:63], v[38:39]
	global_store_dwordx4 v[6:7], v[24:27], off
	global_store_dwordx4 v[6:7], v[28:31], off offset:16
	global_store_dwordx4 v[6:7], v[32:35], off offset:2048
	global_store_dwordx4 v[6:7], v[36:39], off offset:2064
	v_lshl_add_u64 v[6:7], v[6:7], 0, s[8:9]
	s_branch .Lfin_loop
.Lfin_lastB:
	s_waitcnt vmcnt(4)
	v_lshlrev_b32_e32 v24, 16, v64
	v_and_b32_e32 v25, 0xffff0000, v64
	v_lshlrev_b32_e32 v26, 16, v65
	v_and_b32_e32 v27, 0xffff0000, v65
	v_lshlrev_b32_e32 v28, 16, v66
	v_and_b32_e32 v29, 0xffff0000, v66
	v_lshlrev_b32_e32 v30, 16, v67
	v_and_b32_e32 v31, 0xffff0000, v67
	v_lshlrev_b32_e32 v32, 16, v68
	v_and_b32_e32 v33, 0xffff0000, v68
	v_lshlrev_b32_e32 v34, 16, v69
	v_and_b32_e32 v35, 0xffff0000, v69
	v_lshlrev_b32_e32 v36, 16, v70
	v_and_b32_e32 v37, 0xffff0000, v70
	v_lshlrev_b32_e32 v38, 16, v71
	v_and_b32_e32 v39, 0xffff0000, v71
	v_pk_mul_f32 v[42:43], v[24:25], v[24:25]
	v_add_f32_e32 v40, v42, v43
	v_pk_mul_f32 v[42:43], v[26:27], v[26:27]
	v_add_f32_e32 v40, v40, v42
	v_add_f32_e32 v40, v40, v43
	v_pk_mul_f32 v[42:43], v[28:29], v[28:29]
	v_add_f32_e32 v40, v40, v42
	v_add_f32_e32 v40, v40, v43
	v_pk_mul_f32 v[42:43], v[30:31], v[30:31]
	v_add_f32_e32 v40, v40, v42
	v_add_f32_e32 v40, v40, v43
	v_pk_mul_f32 v[42:43], v[32:33], v[32:33]
	v_add_f32_e32 v40, v40, v42
	v_add_f32_e32 v40, v40, v43
	v_pk_mul_f32 v[42:43], v[34:35], v[34:35]
	v_add_f32_e32 v40, v40, v42
	v_add_f32_e32 v40, v40, v43
	v_pk_mul_f32 v[42:43], v[36:37], v[36:37]
	v_add_f32_e32 v40, v40, v42
	v_add_f32_e32 v40, v40, v43
	v_pk_mul_f32 v[42:43], v[38:39], v[38:39]
	v_add_f32_e32 v40, v40, v42
	v_add_f32_e32 v40, v40, v43
	ds_swizzle_b32 v41, v40 offset:swizzle(SWAP,1)
	s_waitcnt lgkmcnt(0)
	v_add_f32_e32 v40, v40, v41
	ds_swizzle_b32 v41, v40 offset:swizzle(SWAP,2)
	s_waitcnt lgkmcnt(0)
	v_add_f32_e32 v40, v40, v41
	ds_swizzle_b32 v41, v40 offset:swizzle(SWAP,4)
	s_waitcnt lgkmcnt(0)
	v_add_f32_e32 v40, v40, v41
	ds_swizzle_b32 v41, v40 offset:swizzle(SWAP,8)
	s_waitcnt lgkmcnt(0)
	v_add_f32_e32 v40, v40, v41
	ds_swizzle_b32 v41, v40 offset:swizzle(SWAP,16)
	s_waitcnt lgkmcnt(0)
	v_add_f32_e32 v40, v40, v41
	v_mov_b32_e32 v41, v40
	s_nop 1
	v_permlane32_swap_b32_e32 v40, v41
	v_add_f32_e32 v40, v40, v41
	v_fmamk_f32 v40, v40, 0x3a800000, v200
	v_rsq_f32_e32 v40, v40
	s_nop 0
	v_pk_mul_f32 v[24:25], v[40:41], v[24:25] op_sel_hi:[0,1]
	v_pk_mul_f32 v[26:27], v[40:41], v[26:27] op_sel_hi:[0,1]
	v_pk_mul_f32 v[28:29], v[40:41], v[28:29] op_sel_hi:[0,1]
	v_pk_mul_f32 v[30:31], v[40:41], v[30:31] op_sel_hi:[0,1]
	v_pk_mul_f32 v[32:33], v[40:41], v[32:33] op_sel_hi:[0,1]
	v_pk_mul_f32 v[34:35], v[40:41], v[34:35] op_sel_hi:[0,1]
	v_pk_mul_f32 v[36:37], v[40:41], v[36:37] op_sel_hi:[0,1]
	v_pk_mul_f32 v[38:39], v[40:41], v[38:39] op_sel_hi:[0,1]
	v_pk_mul_f32 v[24:25], v[48:49], v[24:25]
	v_pk_mul_f32 v[26:27], v[50:51], v[26:27]
	v_pk_mul_f32 v[28:29], v[52:53], v[28:29]
	v_pk_mul_f32 v[30:31], v[54:55], v[30:31]
	v_pk_mul_f32 v[32:33], v[56:57], v[32:33]
	v_pk_mul_f32 v[34:35], v[58:59], v[34:35]
	v_pk_mul_f32 v[36:37], v[60:61], v[36:37]
	v_pk_mul_f32 v[38:39], v[62:63], v[38:39]
	global_store_dwordx4 v[6:7], v[24:27], off
	global_store_dwordx4 v[6:7], v[28:31], off offset:16
	global_store_dwordx4 v[6:7], v[32:35], off offset:2048
	global_store_dwordx4 v[6:7], v[36:39], off offset:2064
	v_lshl_add_u64 v[6:7], v[6:7], 0, s[8:9]
	s_branch .Lfin_done
; __global__ void __launch_bounds__(512, 2) fwd_kernel(Args a) {
;     ...
;             PH_LANES;
;             const float* gn = ap->in[I_NFIN];
;             for (int m = gw; m < MTOK; m += NGW) { const u32x4* hr = (const u32x4*)(H + (size_t)m * DMODEL) + lane; f32x4* xr = (f32x4*)(X + (size_t)m * DMODEL); float v[16]; float s = 0.f;
; #pragma unroll
;                 for (int jj = 0; jj < 2; ++jj) { const u32x4 w = hr[64 * jj];
; #pragma unroll
;                     for (int k = 0; k < 4; ++k) { v[jj * 8 + 2 * k] = __uint_as_float(w[k] << 16); v[jj * 8 + 2 * k + 1] = __uint_as_float(w[k] & 0xffff0000u); } }
; #pragma unroll
;                 for (int k = 0; k < 16; ++k) s += v[k] * v[k];
;                 const float rstd = rsqrtf(wave_sum(s) * (1.0f / DMODEL) + EPS);
; #pragma unroll
;                 for (int jj = 0; jj < 2; ++jj) { const int c4 = 2 * (lane + 64 * jj); const f32x4 g0 = ((const f32x4*)gn)[c4], g1 = ((const f32x4*)gn)[c4 + 1];
;                     xr[c4] = (f32x4){v[jj * 8 + 0] * rstd * g0[0], v[jj * 8 + 1] * rstd * g0[1], v[jj * 8 + 2] * rstd * g0[2], v[jj * 8 + 3] * rstd * g0[3]};
;                     xr[c4 + 1] = (f32x4){v[jj * 8 + 4] * rstd * g1[0], v[jj * 8 + 5] * rstd * g1[1], v[jj * 8 + 6] * rstd * g1[2], v[jj * 8 + 7] * rstd * g1[3]}; } }
.LBB0_400:
	global_load_dwordx4 v[8:11], v[4:5], off
	global_load_dwordx4 v[12:15], v[4:5], off offset:1024
	global_load_dwordx4 v[16:19], v[2:3], off offset:16
	global_load_dwordx4 v[20:23], v[2:3], off
	s_add_i32 s4, s4, s54
	v_lshl_add_u64 v[4:5], v[4:5], 0, s[6:7]
	s_cmp_gt_i32 s4, 0x13fff
	s_waitcnt vmcnt(0)
	v_lshlrev_b32_e32 v24, 16, v8
	v_and_b32_e32 v25, 0xffff0000, v8
	v_lshlrev_b32_e32 v8, 16, v9
	v_and_b32_e32 v9, 0xffff0000, v9
	v_lshlrev_b32_e32 v28, 16, v12
	v_and_b32_e32 v29, 0xffff0000, v12
	v_lshlrev_b32_e32 v30, 16, v13
	v_and_b32_e32 v31, 0xffff0000, v13
	v_pk_mul_f32 v[12:13], v[24:25], v[24:25]
	v_lshlrev_b32_e32 v32, 16, v14
	v_and_b32_e32 v33, 0xffff0000, v14
	v_lshlrev_b32_e32 v34, 16, v15
	v_and_b32_e32 v35, 0xffff0000, v15
	v_pk_mul_f32 v[14:15], v[8:9], v[8:9]
	v_add_f32_e32 v0, v12, v13
	v_lshlrev_b32_e32 v26, 16, v10
	v_and_b32_e32 v27, 0xffff0000, v10
	v_add_f32_e32 v0, v0, v14
	v_pk_mul_f32 v[36:37], v[26:27], v[26:27]
	v_add_f32_e32 v0, v0, v15
	v_lshlrev_b32_e32 v10, 16, v11
	v_and_b32_e32 v11, 0xffff0000, v11
	v_add_f32_e32 v0, v0, v36
	v_pk_mul_f32 v[38:39], v[10:11], v[10:11]
	v_add_f32_e32 v0, v0, v37
	v_add_f32_e32 v0, v0, v38
	v_pk_mul_f32 v[40:41], v[28:29], v[28:29]
	v_add_f32_e32 v0, v0, v39
	v_add_f32_e32 v0, v0, v40
	v_pk_mul_f32 v[42:43], v[30:31], v[30:31]
	v_add_f32_e32 v0, v0, v41
	v_add_f32_e32 v0, v0, v42
	v_pk_mul_f32 v[44:45], v[32:33], v[32:33]
	v_add_f32_e32 v0, v0, v43
	v_add_f32_e32 v0, v0, v44
	v_pk_mul_f32 v[46:47], v[34:35], v[34:35]
	v_add_f32_e32 v0, v0, v45
	v_add_f32_e32 v0, v0, v46
	v_add_f32_e32 v0, v0, v47
	ds_swizzle_b32 v12, v0 offset:swizzle(SWAP,1)
	s_waitcnt lgkmcnt(0)
	v_add_f32_e32 v0, v0, v12
	ds_swizzle_b32 v12, v0 offset:swizzle(SWAP,2)
	s_waitcnt lgkmcnt(0)
	v_add_f32_e32 v0, v0, v12
	ds_swizzle_b32 v12, v0 offset:swizzle(SWAP,4)
	s_waitcnt lgkmcnt(0)
	v_add_f32_e32 v0, v0, v12
	ds_swizzle_b32 v12, v0 offset:swizzle(SWAP,8)
	s_waitcnt lgkmcnt(0)
	v_add_f32_e32 v0, v0, v12
	ds_swizzle_b32 v12, v0 offset:swizzle(SWAP,16)
	s_waitcnt lgkmcnt(0)
	v_add_f32_e32 v0, v0, v12
	v_mov_b32_e32 v12, v0
	s_nop 1
	v_permlane32_swap_b32_e32 v0, v12
	v_add_f32_e32 v0, v0, v12
	v_fmamk_f32 v0, v0, 0x3a800000, v200
	v_mul_f32_e32 v12, 0x4b800000, v0
	v_cmp_gt_f32_e32 vcc, s44, v0
	s_nop 1
	v_cndmask_b32_e32 v0, v0, v12, vcc
	v_rsq_f32_e32 v0, v0
	s_nop 0
	v_mul_f32_e32 v12, 0x45800000, v0
	v_cndmask_b32_e32 v0, v0, v12, vcc
	v_pk_mul_f32 v[12:13], v[0:1], v[24:25] op_sel_hi:[0,1]
	v_pk_mul_f32 v[8:9], v[0:1], v[8:9] op_sel_hi:[0,1]
	v_pk_mul_f32 v[24:25], v[0:1], v[26:27] op_sel_hi:[0,1]
	v_pk_mul_f32 v[14:15], v[0:1], v[10:11] op_sel_hi:[0,1]
	v_pk_mul_f32 v[10:11], v[22:23], v[8:9]
	v_pk_mul_f32 v[8:9], v[20:21], v[12:13]
	v_pk_mul_f32 v[14:15], v[18:19], v[14:15]
	v_pk_mul_f32 v[12:13], v[16:17], v[24:25]
	global_store_dwordx4 v[6:7], v[8:11], off
	global_store_dwordx4 v[6:7], v[12:15], off offset:16
	global_load_dwordx4 v[8:11], v[2:3], off offset:2048
	s_nop 0
	global_load_dwordx4 v[12:15], v[2:3], off offset:2064
	v_pk_mul_f32 v[16:17], v[0:1], v[30:31] op_sel_hi:[0,1]
	v_pk_mul_f32 v[18:19], v[0:1], v[28:29] op_sel_hi:[0,1]
	v_pk_mul_f32 v[20:21], v[0:1], v[34:35] op_sel_hi:[0,1]
	v_pk_mul_f32 v[22:23], v[0:1], v[32:33] op_sel_hi:[0,1]
	s_waitcnt vmcnt(1)
	v_pk_mul_f32 v[8:9], v[8:9], v[18:19]
	v_pk_mul_f32 v[10:11], v[10:11], v[16:17]
	s_waitcnt vmcnt(0)
	v_pk_mul_f32 v[12:13], v[12:13], v[22:23]
	v_pk_mul_f32 v[14:15], v[14:15], v[20:21]
	global_store_dwordx4 v[6:7], v[8:11], off offset:2048
	global_store_dwordx4 v[6:7], v[12:15], off offset:2064
	v_lshl_add_u64 v[6:7], v[6:7], 0, s[8:9]
	s_cbranch_scc0 .LBB0_400
.Lfin_done:
	v_readlane_b32 s72, v252, 13
	v_readlane_b32 s74, v252, 15
	v_readlane_b32 s73, v252, 14
	v_readlane_b32 s75, v252, 16
.LBB0_402:
	s_cbranch_execnz .LBB0_25

; __device__ __forceinline__ unsigned pk2(float lo, float hi) { f32x2_t v = {lo, hi}; bf16x2_t b = __builtin_convertvector(v, bf16x2_t); return __builtin_bit_cast(unsigned, b); }
; __device__ __forceinline__ void rms_rows(const float* __restrict__ xa, const float* __restrict__ xb, int nrows_a, int nrows, bf16_t* __restrict__ H, int gw, int NGW, int lane) {
;     for (int m = gw; m < nrows; m += NGW) {
;         const float* xr = m < nrows_a ? xa + (size_t)m * DMODEL : xb + (size_t)(m - nrows_a) * DMODEL;
;         f32x4 v[4]; float s = 0.f;
; #pragma unroll
;         for (int j = 0; j < 4; ++j) { v[j] = ((const f32x4*)xr)[lane + 64 * j]; s += (v[j][0] * v[j][0] + v[j][1] * v[j][1]) + (v[j][2] * v[j][2] + v[j][3] * v[j][3]); }
;         const float rstd = rsqrtf(wave_sum(s) * (1.0f / DMODEL) + EPS);
;         u32x2* o = (u32x2*)(H + (size_t)m * DMODEL) + lane;
; #pragma unroll
;         for (int j = 0; j < 4; ++j) { u32x2 w; w.x = pk2(v[j][0] * rstd, v[j][1] * rstd); w.y = pk2(v[j][2] * rstd, v[j][3] * rstd); o[64 * j] = w; }
;     }
.LBB0_563:
	s_cmp_gt_i32 s14, 0x13fff
	s_cbranch_scc1 .LBB0_568
	s_load_dwordx4 s[8:11], s[50:51], 0x0
	s_ashr_i32 s15, s14, 31
	s_ashr_i32 s55, s54, 31
	s_lshl_b64 s[4:5], s[14:15], 12
	v_lshlrev_b32_e32 v0, 3, v2
	s_waitcnt lgkmcnt(0)
	s_add_u32 s4, s8, s4
	v_lshl_add_u64 v[4:5], s[60:61], 0, v[0:1]
	s_addc_u32 s5, s9, s5
	s_lshl_b64 s[6:7], s[54:55], 12
	v_lshlrev_b32_e32 v0, 4, v2
	s_cmpk_lg_i32 s54, 0x800
	s_cbranch_scc1 .LBB0_566
	s_cmpk_lt_i32 s14, 0x4000
	s_cselect_b32 s16, s8, s10
	s_cselect_b32 s17, s9, s11
	s_cselect_b32 s28, 0, 0x4000
	s_sub_i32 s28, s14, s28
	s_lshl_b64 s[18:19], s[28:29], 12
	s_add_u32 s16, s16, s18
	s_addc_u32 s17, s17, s19
	global_load_dwordx4 v[6:9], v0, s[16:17]
	global_load_dwordx4 v[10:13], v0, s[16:17] offset:1024
	global_load_dwordx4 v[14:17], v0, s[16:17] offset:2048
	global_load_dwordx4 v[18:21], v0, s[16:17] offset:3072
	s_mov_b32 s20, s14
	s_addk_i32 s14, 0x800
	s_movk_i32 s21, 20
	s_cmpk_lt_i32 s14, 0x4000
	s_cselect_b32 s16, s8, s10
	s_cselect_b32 s17, s9, s11
	s_cselect_b32 s28, 0, 0x4000
	s_sub_i32 s28, s14, s28
	s_lshl_b64 s[18:19], s[28:29], 12
	s_add_u32 s16, s16, s18
	s_addc_u32 s17, s17, s19
	global_load_dwordx4 v[48:51], v0, s[16:17]
	global_load_dwordx4 v[52:55], v0, s[16:17] offset:1024
	global_load_dwordx4 v[56:59], v0, s[16:17] offset:2048
	global_load_dwordx4 v[60:63], v0, s[16:17] offset:3072
	s_mov_b32 s22, s14
	s_addk_i32 s14, 0x800
	s_waitcnt vmcnt(4)
	s_branch .Lprm_first
.Lprm_loop:
	s_cmpk_lt_i32 s14, 0x4000
	s_cselect_b32 s16, s8, s10
	s_cselect_b32 s17, s9, s11
	s_cselect_b32 s28, 0, 0x4000
	s_sub_i32 s28, s14, s28
	s_lshl_b64 s[18:19], s[28:29], 12
	s_add_u32 s16, s16, s18
	s_addc_u32 s17, s17, s19
	global_load_dwordx4 v[48:51], v0, s[16:17]
	global_load_dwordx4 v[52:55], v0, s[16:17] offset:1024
	global_load_dwordx4 v[56:59], v0, s[16:17] offset:2048
	global_load_dwordx4 v[60:63], v0, s[16:17] offset:3072
	s_mov_b32 s22, s14
	s_addk_i32 s14, 0x800
	s_waitcnt vmcnt(8)
.Lprm_first:
	s_mov_b32 s15, s20
	v_mul_f32_e32 v22, v6, v6
	v_fmac_f32_e32 v22, v7, v7
	v_fmac_f32_e32 v22, v8, v8
	v_fmac_f32_e32 v22, v9, v9
	v_fmac_f32_e32 v22, v10, v10
	v_fmac_f32_e32 v22, v11, v11
	v_fmac_f32_e32 v22, v12, v12
	v_fmac_f32_e32 v22, v13, v13
	v_fmac_f32_e32 v22, v14, v14
	v_fmac_f32_e32 v22, v15, v15
	v_fmac_f32_e32 v22, v16, v16
	v_fmac_f32_e32 v22, v17, v17
	v_fmac_f32_e32 v22, v18, v18
	v_fmac_f32_e32 v22, v19, v19
	v_fmac_f32_e32 v22, v20, v20
	v_fmac_f32_e32 v22, v21, v21
	ds_swizzle_b32 v23, v22 offset:swizzle(SWAP,1)
	s_waitcnt lgkmcnt(0)
	v_add_f32_e32 v22, v22, v23
	ds_swizzle_b32 v23, v22 offset:swizzle(SWAP,2)
	s_waitcnt lgkmcnt(0)
	v_add_f32_e32 v22, v22, v23
	ds_swizzle_b32 v23, v22 offset:swizzle(SWAP,4)
	s_waitcnt lgkmcnt(0)
	v_add_f32_e32 v22, v22, v23
	ds_swizzle_b32 v23, v22 offset:swizzle(SWAP,8)
	s_waitcnt lgkmcnt(0)
	v_add_f32_e32 v22, v22, v23
	ds_swizzle_b32 v23, v22 offset:swizzle(SWAP,16)
	s_waitcnt lgkmcnt(0)
	v_add_f32_e32 v22, v22, v23
	v_mov_b32_e32 v23, v22
	s_nop 1
	v_permlane32_swap_b32_e32 v22, v23
	v_add_f32_e32 v22, v22, v23
	v_fmamk_f32 v22, v22, 0x3a800000, v200
	v_rsq_f32_e32 v22, v22
	s_lshl_b32 s18, s15, 11
	s_mov_b32 s19, 0
	v_lshl_add_u64 v[2:3], v[4:5], 0, s[18:19]
	v_pk_mul_f32 v[6:7], v[6:7], v[22:23] op_sel_hi:[1,0]
	v_pk_mul_f32 v[8:9], v[8:9], v[22:23] op_sel_hi:[1,0]
	v_pk_mul_f32 v[10:11], v[10:11], v[22:23] op_sel_hi:[1,0]
	v_pk_mul_f32 v[12:13], v[12:13], v[22:23] op_sel_hi:[1,0]
	v_pk_mul_f32 v[14:15], v[14:15], v[22:23] op_sel_hi:[1,0]
	v_pk_mul_f32 v[16:17], v[16:17], v[22:23] op_sel_hi:[1,0]
	v_pk_mul_f32 v[18:19], v[18:19], v[22:23] op_sel_hi:[1,0]
	v_pk_mul_f32 v[20:21], v[20:21], v[22:23] op_sel_hi:[1,0]
	v_cvt_pk_bf16_f32 v6, v6, v7
	v_cvt_pk_bf16_f32 v7, v8, v9
	v_cvt_pk_bf16_f32 v8, v10, v11
	v_cvt_pk_bf16_f32 v9, v12, v13
	v_cvt_pk_bf16_f32 v10, v14, v15
	v_cvt_pk_bf16_f32 v11, v16, v17
	v_cvt_pk_bf16_f32 v12, v18, v19
	v_cvt_pk_bf16_f32 v13, v20, v21
	global_store_dwordx2 v[2:3], v[6:7], off
	global_store_dwordx2 v[2:3], v[8:9], off offset:512
	global_store_dwordx2 v[2:3], v[10:11], off offset:1024
	global_store_dwordx2 v[2:3], v[12:13], off offset:1536
	s_sub_i32 s21, s21, 1
	s_cmp_eq_u32 s21, 0
	s_cbranch_scc1 .Lprm_last
	s_cmpk_lt_i32 s14, 0x4000
	s_cselect_b32 s16, s8, s10
	s_cselect_b32 s17, s9, s11
	s_cselect_b32 s28, 0, 0x4000
	s_sub_i32 s28, s14, s28
	s_lshl_b64 s[18:19], s[28:29], 12
	s_add_u32 s16, s16, s18
	s_addc_u32 s17, s17, s19
	global_load_dwordx4 v[6:9], v0, s[16:17]
	global_load_dwordx4 v[10:13], v0, s[16:17] offset:1024
	global_load_dwordx4 v[14:17], v0, s[16:17] offset:2048
	global_load_dwordx4 v[18:21], v0, s[16:17] offset:3072
	s_mov_b32 s20, s14
	s_addk_i32 s14, 0x800
	s_waitcnt vmcnt(8)
	s_mov_b32 s15, s22
	v_mul_f32_e32 v22, v48, v48
	v_fmac_f32_e32 v22, v49, v49
	v_fmac_f32_e32 v22, v50, v50
	v_fmac_f32_e32 v22, v51, v51
	v_fmac_f32_e32 v22, v52, v52
	v_fmac_f32_e32 v22, v53, v53
	v_fmac_f32_e32 v22, v54, v54
	v_fmac_f32_e32 v22, v55, v55
	v_fmac_f32_e32 v22, v56, v56
	v_fmac_f32_e32 v22, v57, v57
	v_fmac_f32_e32 v22, v58, v58
	v_fmac_f32_e32 v22, v59, v59
	v_fmac_f32_e32 v22, v60, v60
	v_fmac_f32_e32 v22, v61, v61
	v_fmac_f32_e32 v22, v62, v62
	v_fmac_f32_e32 v22, v63, v63
	ds_swizzle_b32 v23, v22 offset:swizzle(SWAP,1)
	s_waitcnt lgkmcnt(0)
	v_add_f32_e32 v22, v22, v23
	ds_swizzle_b32 v23, v22 offset:swizzle(SWAP,2)
	s_waitcnt lgkmcnt(0)
	v_add_f32_e32 v22, v22, v23
	ds_swizzle_b32 v23, v22 offset:swizzle(SWAP,4)
	s_waitcnt lgkmcnt(0)
	v_add_f32_e32 v22, v22, v23
	ds_swizzle_b32 v23, v22 offset:swizzle(SWAP,8)
	s_waitcnt lgkmcnt(0)
	v_add_f32_e32 v22, v22, v23
	ds_swizzle_b32 v23, v22 offset:swizzle(SWAP,16)
	s_waitcnt lgkmcnt(0)
	v_add_f32_e32 v22, v22, v23
	v_mov_b32_e32 v23, v22
	s_nop 1
	v_permlane32_swap_b32_e32 v22, v23
	v_add_f32_e32 v22, v22, v23
	v_fmamk_f32 v22, v22, 0x3a800000, v200
	v_rsq_f32_e32 v22, v22
	s_lshl_b32 s18, s15, 11
	s_mov_b32 s19, 0
	v_lshl_add_u64 v[2:3], v[4:5], 0, s[18:19]
	v_pk_mul_f32 v[48:49], v[48:49], v[22:23] op_sel_hi:[1,0]
	v_pk_mul_f32 v[50:51], v[50:51], v[22:23] op_sel_hi:[1,0]
	v_pk_mul_f32 v[52:53], v[52:53], v[22:23] op_sel_hi:[1,0]
	v_pk_mul_f32 v[54:55], v[54:55], v[22:23] op_sel_hi:[1,0]
	v_pk_mul_f32 v[56:57], v[56:57], v[22:23] op_sel_hi:[1,0]
	v_pk_mul_f32 v[58:59], v[58:59], v[22:23] op_sel_hi:[1,0]
	v_pk_mul_f32 v[60:61], v[60:61], v[22:23] op_sel_hi:[1,0]
	v_pk_mul_f32 v[62:63], v[62:63], v[22:23] op_sel_hi:[1,0]
	v_cvt_pk_bf16_f32 v48, v48, v49
	v_cvt_pk_bf16_f32 v49, v50, v51
	v_cvt_pk_bf16_f32 v50, v52, v53
	v_cvt_pk_bf16_f32 v51, v54, v55
	v_cvt_pk_bf16_f32 v52, v56, v57
	v_cvt_pk_bf16_f32 v53, v58, v59
	v_cvt_pk_bf16_f32 v54, v60, v61
	v_cvt_pk_bf16_f32 v55, v62, v63
	global_store_dwordx2 v[2:3], v[48:49], off
	global_store_dwordx2 v[2:3], v[50:51], off offset:512
	global_store_dwordx2 v[2:3], v[52:53], off offset:1024
	global_store_dwordx2 v[2:3], v[54:55], off offset:1536
	s_branch .Lprm_loop
; __device__ __forceinline__ unsigned pk2(float lo, float hi) { f32x2_t v = {lo, hi}; bf16x2_t b = __builtin_convertvector(v, bf16x2_t); return __builtin_bit_cast(unsigned, b); }
; __device__ __forceinline__ void rms_rows(const float* __restrict__ xa, const float* __restrict__ xb, int nrows_a, int nrows, bf16_t* __restrict__ H, int gw, int NGW, int lane) {
;     for (int m = gw; m < nrows; m += NGW) {
;         const float* xr = m < nrows_a ? xa + (size_t)m * DMODEL : xb + (size_t)(m - nrows_a) * DMODEL;
;         f32x4 v[4]; float s = 0.f;
; #pragma unroll
;         for (int j = 0; j < 4; ++j) { v[j] = ((const f32x4*)xr)[lane + 64 * j]; s += (v[j][0] * v[j][0] + v[j][1] * v[j][1]) + (v[j][2] * v[j][2] + v[j][3] * v[j][3]); }
;         const float rstd = rsqrtf(wave_sum(s) * (1.0f / DMODEL) + EPS);
;         u32x2* o = (u32x2*)(H + (size_t)m * DMODEL) + lane;
; #pragma unroll
;         for (int j = 0; j < 4; ++j) { u32x2 w; w.x = pk2(v[j][0] * rstd, v[j][1] * rstd); w.y = pk2(v[j][2] * rstd, v[j][3] * rstd); o[64 * j] = w; }
;     }
.Lprm_last:
	s_waitcnt vmcnt(4)
	s_mov_b32 s15, s22
	v_mul_f32_e32 v22, v48, v48
	v_fmac_f32_e32 v22, v49, v49
	v_fmac_f32_e32 v22, v50, v50
	v_fmac_f32_e32 v22, v51, v51
	v_fmac_f32_e32 v22, v52, v52
	v_fmac_f32_e32 v22, v53, v53
	v_fmac_f32_e32 v22, v54, v54
	v_fmac_f32_e32 v22, v55, v55
	v_fmac_f32_e32 v22, v56, v56
	v_fmac_f32_e32 v22, v57, v57
	v_fmac_f32_e32 v22, v58, v58
	v_fmac_f32_e32 v22, v59, v59
	v_fmac_f32_e32 v22, v60, v60
	v_fmac_f32_e32 v22, v61, v61
	v_fmac_f32_e32 v22, v62, v62
	v_fmac_f32_e32 v22, v63, v63
	ds_swizzle_b32 v23, v22 offset:swizzle(SWAP,1)
	s_waitcnt lgkmcnt(0)
	v_add_f32_e32 v22, v22, v23
	ds_swizzle_b32 v23, v22 offset:swizzle(SWAP,2)
	s_waitcnt lgkmcnt(0)
	v_add_f32_e32 v22, v22, v23
	ds_swizzle_b32 v23, v22 offset:swizzle(SWAP,4)
	s_waitcnt lgkmcnt(0)
	v_add_f32_e32 v22, v22, v23
	ds_swizzle_b32 v23, v22 offset:swizzle(SWAP,8)
	s_waitcnt lgkmcnt(0)
	v_add_f32_e32 v22, v22, v23
	ds_swizzle_b32 v23, v22 offset:swizzle(SWAP,16)
	s_waitcnt lgkmcnt(0)
	v_add_f32_e32 v22, v22, v23
	v_mov_b32_e32 v23, v22
	s_nop 1
	v_permlane32_swap_b32_e32 v22, v23
	v_add_f32_e32 v22, v22, v23
	v_fmamk_f32 v22, v22, 0x3a800000, v200
	v_rsq_f32_e32 v22, v22
	s_lshl_b32 s18, s15, 11
	s_mov_b32 s19, 0
	v_lshl_add_u64 v[2:3], v[4:5], 0, s[18:19]
	v_pk_mul_f32 v[48:49], v[48:49], v[22:23] op_sel_hi:[1,0]
	v_pk_mul_f32 v[50:51], v[50:51], v[22:23] op_sel_hi:[1,0]
	v_pk_mul_f32 v[52:53], v[52:53], v[22:23] op_sel_hi:[1,0]
	v_pk_mul_f32 v[54:55], v[54:55], v[22:23] op_sel_hi:[1,0]
	v_pk_mul_f32 v[56:57], v[56:57], v[22:23] op_sel_hi:[1,0]
	v_pk_mul_f32 v[58:59], v[58:59], v[22:23] op_sel_hi:[1,0]
	v_pk_mul_f32 v[60:61], v[60:61], v[22:23] op_sel_hi:[1,0]
	v_pk_mul_f32 v[62:63], v[62:63], v[22:23] op_sel_hi:[1,0]
	v_cvt_pk_bf16_f32 v48, v48, v49
	v_cvt_pk_bf16_f32 v49, v50, v51
	v_cvt_pk_bf16_f32 v50, v52, v53
	v_cvt_pk_bf16_f32 v51, v54, v55
	v_cvt_pk_bf16_f32 v52, v56, v57
	v_cvt_pk_bf16_f32 v53, v58, v59
	v_cvt_pk_bf16_f32 v54, v60, v61
	v_cvt_pk_bf16_f32 v55, v62, v63
	global_store_dwordx2 v[2:3], v[48:49], off
	global_store_dwordx2 v[2:3], v[50:51], off offset:512
	global_store_dwordx2 v[2:3], v[52:53], off offset:1024
	global_store_dwordx2 v[2:3], v[54:55], off offset:1536
	s_branch .LBB0_568
